# prompt-unit epilogues: with the closing barrier no longer draining vmcnt, the source's own counted waits pace the 6 preloaded values (my extra vmcnt(0) removed)
# speedup vs baseline: 1.0040x; 1.0003x over previous
; #define ATT_WAIT_BAR() asm volatile("s_waitcnt vmcnt(0) lgkmcnt(0)\n\ts_barrier" ::: "memory")
; template <int TYPE>
; __device__ __forceinline__ void epi_preload(EpiPre& e, const Args& a, int l, int h, size_t rowq, int col, int lane) {
;     const int ch = lane & 7;
;     const float* gp = (TYPE == 0 ? a.gn_a : a.gn_b) + (size_t)l * W + h * HD + ch * 8;
;     e.g0 = *(const f32x4*)gp; e.g1 = *(const f32x4*)(gp + 4);
; #pragma unroll
;     for (int i = 0; i < 4; ++i) e.z[i] = *(const u32x4*)((const bf16*)(a.ws + WS_Z) + (rowq + i * 8 + (lane >> 3)) * D + col + ch * 8);
; }
; __device__ __forceinline__ void prompt_unit_sb(const Args& a, int l, int b, int h, int qb, LAS unsigned char* lds) {
;     ...
;     EpiPre pre; epi_preload<1>(pre, a, l, h, rowb + q0 + wid * 32, col, lane);
;     ATT_WAIT_BAR();
.LBB0_300:
	v_readlane_b32 s4, v242, 28
	v_readlane_b32 s5, v242, 29
	s_mov_b32 s1, s87
	v_lshlrev_b32_e32 v4, 1, v168
	v_lshl_add_u64 v[2:3], s[4:5], 0, v[166:167]
	v_lshl_add_u64 v[2:3], v[2:3], 0, s[0:1]
	v_lshl_add_u64 v[2:3], v[2:3], 0, v[4:5]
	global_load_dwordx4 v[60:63], v[2:3], off offset:1024
	v_readlane_b32 s4, v242, 12
	v_readlane_b32 s6, v242, 14
	v_readlane_b32 s5, v242, 13
	v_readlane_b32 s7, v242, 15
	s_add_u32 s4, s6, s92
	v_lshlrev_b32_e32 v3, 2, v168
	s_addc_u32 s5, s7, 0
	v_readlane_b32 s6, v242, 30
	global_load_dwordx4 v[14:17], v3, s[4:5]
	v_readlane_b32 s7, v242, 31
	s_lshl_b32 s3, s82, 13
	v_lshlrev_b32_e32 v68, 2, v169
	v_lshl_add_u64 v[6:7], s[6:7], 0, v[166:167]
	v_readlane_b32 s6, v242, 32
	v_readlane_b32 s7, v242, 33
	s_add_i32 s3, s3, 0
	v_readlane_b32 s10, v242, 36
	v_lshl_add_u64 v[8:9], s[6:7], 0, v[166:167]
	v_readlane_b32 s6, v242, 34
	v_readlane_b32 s7, v242, 35
	v_lshl_add_u64 v[6:7], v[6:7], 0, s[0:1]
	v_lshl_add_u64 v[8:9], v[8:9], 0, s[0:1]
	v_lshl_add_u64 v[10:11], s[6:7], 0, v[166:167]
	v_lshl_add_u64 v[52:53], v[10:11], 0, s[0:1]
	global_load_dwordx4 v[10:13], v3, s[4:5] offset:16
	v_add3_u32 v3, s3, v171, v68
	v_and_b32_e32 v2, 7, v19
	v_readlane_b32 s11, v242, 37
	v_lshl_add_u64 v[6:7], v[6:7], 0, v[4:5]
	v_lshl_add_u64 v[8:9], v[8:9], 0, v[4:5]
	v_lshl_add_u64 v[66:67], v[52:53], 0, v[4:5]
	v_add_u32_e32 v4, 0x800, v3
	v_lshl_add_u64 v[64:65], s[10:11], 0, v[166:167]
	global_load_dwordx4 v[56:59], v[6:7], off offset:1024
	global_load_dwordx4 v[52:55], v[8:9], off offset:1024
	s_nop 0
	global_load_dwordx4 v[6:9], v[66:67], off offset:1024
	s_waitcnt vmcnt(6) lgkmcnt(0)
	s_barrier
; #define LAS __attribute__((address_space(3)))
; __device__ __forceinline__ float bflo(unsigned w) { return __uint_as_float(w << 16); }
; __device__ __forceinline__ float bfhi(unsigned w) { return __uint_as_float(w & 0xffff0000u); }
; __device__ __forceinline__ int crow(int r, int hi) { return (r & 3) + 8 * (r >> 2) + 4 * hi; }
; __device__ __forceinline__ unsigned cvtpk(float lo, float hi) { f32x2 v = {lo, hi}; bf16x2_t b = __builtin_convertvector(v, bf16x2_t); return __builtin_bit_cast(unsigned, b); }
; #define ATT_LDS_WAIT() asm volatile("s_waitcnt lgkmcnt(0)" ::: "memory")
; __device__ __forceinline__ float gate8(const f32x4& x0, const f32x4& x1, const float (&gn)[8], const u32x4& zw, bf16* orow) {
;     const float zz[8] = {bflo(zw.x), bfhi(zw.x), bflo(zw.y), bfhi(zw.y), bflo(zw.z), bfhi(zw.z), bflo(zw.w), bfhi(zw.w)};
;     const float xs[8] = {x0[0], x0[1], x0[2], x0[3], x1[0], x1[1], x1[2], x1[3]};
;     float r[8], ssq = 0.f;
; #pragma unroll
;     for (int i = 0; i < 8; ++i) { ssq += xs[i] * xs[i]; r[i] = xs[i] * gn[i] * (zz[i] / (1.0f + __expf(-zz[i]))); }
;     u32x4 w; w.x = cvtpk(r[0], r[1]); w.y = cvtpk(r[2], r[3]); w.z = cvtpk(r[4], r[5]); w.w = cvtpk(r[6], r[7]);
;     *(u32x4*)orow = w;
;     return ssq;
; template <int TYPE>
; __device__ __forceinline__ void prompt_epilogue(const Args& a, int l, int h, size_t rowq  , int col, FoxState& st, const EpiPre& pre, LAS float* wsf, LAS float* stg, int lane, int r32, int hi) {
;     ...
; #pragma unroll
;     for (int r = 0; r < 16; ++r) { stg[crow(r, hi) * 64 + r32] = st.o[0][r]; stg[crow(r, hi) * 64 + 32 + r32] = st.o[1][r]; }
;     ATT_LDS_WAIT();
;     const int ch = lane & 7;
;     const float gn[8] = {pre.g0[0], pre.g0[1], pre.g0[2], pre.g0[3], pre.g1[0], pre.g1[1], pre.g1[2], pre.g1[3]};
; #pragma unroll
;     for (int i = 0; i < 4; ++i) {
;         const int row = i * 8 + (lane >> 3); const size_t grow = rowq + row;
;         const f32x4 x0 = *(const LAS f32x4*)(stg + row * 64 + ch * 8), x1 = *(const LAS f32x4*)(stg + row * 64 + ch * 8 + 4);
;         float ssq = gate8(x0, x1, gn, pre.z[i], (bf16*)(a.ws + WS_HN) + grow * D + col + ch * 8);
;         ssq = sum8_dpp(ssq);
;         if (ch == 0) ((float*)(a.ws + WS_SSQ))[grow * 16 + TYPE * 8 + h] = ssq;
;     }
	v_lshl_add_u32 v19, v2, 5, s3
	ds_write2_b32 v3, v20, v36 offset1:32
	ds_write2_b32 v3, v21, v37 offset0:64 offset1:96
	ds_write2_b32 v3, v22, v38 offset0:128 offset1:160
	ds_write2_b32 v3, v23, v39 offset0:192 offset1:224
	v_add_u32_e32 v20, 0x1000, v3
	v_add_u32_e32 v3, 0x1800, v3
	ds_write2_b32 v4, v24, v40 offset1:32
	ds_write2_b32 v4, v25, v41 offset0:64 offset1:96
	ds_write2_b32 v4, v26, v42 offset0:128 offset1:160
	ds_write2_b32 v4, v27, v43 offset0:192 offset1:224
	ds_write2_b32 v20, v28, v44 offset1:32
	ds_write2_b32 v20, v29, v45 offset0:64 offset1:96
	ds_write2_b32 v20, v30, v46 offset0:128 offset1:160
	ds_write2_b32 v20, v31, v47 offset0:192 offset1:224
	ds_write2_b32 v3, v32, v48 offset1:32
	ds_write2_b32 v3, v33, v49 offset0:64 offset1:96
	ds_write2_b32 v3, v34, v50 offset0:128 offset1:160
	ds_write2_b32 v3, v35, v51 offset0:192 offset1:224
	v_lshl_add_u32 v36, v1, 8, v19
	s_waitcnt lgkmcnt(0)
	v_lshl_add_u64 v[24:25], v[64:65], 0, s[0:1]
	v_lshlrev_b32_e32 v4, 4, v2
	ds_read_b128 v[20:23], v36
	v_lshl_add_u64 v[28:29], v[24:25], 0, v[4:5]
	ds_read_b128 v[24:27], v36 offset:16
	v_cmp_eq_u32_e64 s[6:7], 0, v2
	s_waitcnt lgkmcnt(1)
	v_mul_f32_e32 v3, v21, v21
	v_fmac_f32_e32 v3, v20, v20
	v_fmac_f32_e32 v3, v22, v22
	v_fmac_f32_e32 v3, v23, v23
	s_waitcnt lgkmcnt(0)
	v_fmac_f32_e32 v3, v24, v24
	v_fmac_f32_e32 v3, v25, v25
	v_fmac_f32_e32 v3, v26, v26
	v_fmac_f32_e32 v3, v27, v27
	s_waitcnt vmcnt(5)
	v_lshlrev_b32_e32 v4, 16, v60
	v_and_b32_e32 v36, 0xffff0000, v60
	v_mul_f32_e32 v30, 0xbfb8aa3b, v4
	v_mul_f32_e32 v31, 0xbfb8aa3b, v36
	v_exp_f32_e32 v30, v30
	v_exp_f32_e32 v31, v31
	v_lshlrev_b32_e32 v37, 16, v61
	v_and_b32_e32 v38, 0xffff0000, v61
	v_mul_f32_e32 v32, 0xbfb8aa3b, v37
	v_pk_add_f32 v[30:31], v[30:31], 1.0 op_sel_hi:[1,0]
	v_mul_f32_e32 v33, 0xbfb8aa3b, v38
	v_div_scale_f32 v39, s[4:5], v31, v31, v36
	v_div_scale_f32 v41, s[4:5], v30, v30, v4
	v_rcp_f32_e32 v42, v39
	v_rcp_f32_e32 v43, v41
	v_div_scale_f32 v40, vcc, v36, v31, v36
	v_fma_f32 v45, -v39, v42, 1.0
	v_fma_f32 v46, -v41, v43, 1.0
	v_fmac_f32_e32 v42, v45, v42
	v_div_scale_f32 v44, s[8:9], v4, v30, v4
	v_fmac_f32_e32 v43, v46, v43
	v_mul_f32_e32 v45, v40, v42
	v_exp_f32_e32 v32, v32
	v_exp_f32_e32 v33, v33
	v_mul_f32_e32 v46, v44, v43
	v_fma_f32 v47, -v39, v45, v40
	v_fma_f32 v48, -v41, v46, v44
	v_fmac_f32_e32 v45, v47, v42
	v_fmac_f32_e32 v46, v48, v43
	v_fma_f32 v39, -v39, v45, v40
	v_fma_f32 v40, -v41, v46, v44
	v_div_fmas_f32 v39, v39, v42, v45
	s_mov_b64 vcc, s[8:9]
	v_pk_add_f32 v[32:33], v[32:33], 1.0 op_sel_hi:[1,0]
	v_div_fixup_f32 v31, v39, v31, v36
	v_div_fmas_f32 v36, v40, v43, v46
	v_div_fixup_f32 v30, v36, v30, v4
	v_div_scale_f32 v4, s[4:5], v33, v33, v38
	v_rcp_f32_e32 v36, v4
	s_waitcnt vmcnt(4)
	v_pk_mul_f32 v[34:35], v[16:17], v[22:23]
	v_pk_mul_f32 v[20:21], v[14:15], v[20:21]
	v_and_b32_e32 v40, 0xffff0000, v63
	v_fma_f32 v22, -v4, v36, 1.0
	v_fmac_f32_e32 v36, v22, v36
	v_div_scale_f32 v22, vcc, v38, v33, v38
	v_mul_f32_e32 v23, v22, v36
	v_pk_mul_f32 v[20:21], v[30:31], v[20:21]
	v_fma_f32 v30, -v4, v23, v22
	v_fmac_f32_e32 v23, v30, v36
	v_fma_f32 v4, -v4, v23, v22
	v_div_scale_f32 v22, s[4:5], v32, v32, v37
	v_rcp_f32_e32 v30, v22
	v_div_fmas_f32 v4, v4, v36, v23
	v_div_fixup_f32 v23, v4, v33, v38
	v_lshlrev_b32_e32 v36, 16, v62
	v_fma_f32 v4, -v22, v30, 1.0
	v_fmac_f32_e32 v30, v4, v30
	v_div_scale_f32 v4, vcc, v37, v32, v37
	v_mul_f32_e32 v31, v4, v30
	v_fma_f32 v33, -v22, v31, v4
	v_fmac_f32_e32 v31, v33, v30
	v_fma_f32 v4, -v22, v31, v4
	v_and_b32_e32 v38, 0xffff0000, v62
	v_mul_f32_e32 v22, 0xbfb8aa3b, v36
	v_div_fmas_f32 v4, v4, v30, v31
	v_exp_f32_e32 v30, v22
	v_mul_f32_e32 v22, 0xbfb8aa3b, v38
	v_exp_f32_e32 v31, v22
	v_div_fixup_f32 v22, v4, v32, v37
	v_pk_mul_f32 v[22:23], v[22:23], v[34:35]
	s_waitcnt vmcnt(3)
	v_pk_mul_f32 v[32:33], v[12:13], v[26:27]
	v_pk_add_f32 v[30:31], v[30:31], 1.0 op_sel_hi:[1,0]
	v_pk_mul_f32 v[24:25], v[10:11], v[24:25]
	v_div_scale_f32 v4, s[4:5], v31, v31, v38
	v_rcp_f32_e32 v34, v4
	v_add_f32_dpp v3, v3, v3 quad_perm:[1,0,3,2] row_mask:0xf bank_mask:0xf bound_ctrl:1
	v_cvt_pk_bf16_f32 v20, v20, v21
	v_cvt_pk_bf16_f32 v21, v22, v23
	v_fma_f32 v35, -v4, v34, 1.0
	v_fmac_f32_e32 v34, v35, v34
	v_div_scale_f32 v35, vcc, v38, v31, v38
	v_mul_f32_e32 v37, v35, v34
	v_fma_f32 v39, -v4, v37, v35
	v_fmac_f32_e32 v37, v39, v34
	v_fma_f32 v4, -v4, v37, v35
	v_div_scale_f32 v35, s[4:5], v30, v30, v36
	v_rcp_f32_e32 v39, v35
	v_div_fmas_f32 v4, v4, v34, v37
	v_div_fixup_f32 v31, v4, v31, v38
	v_lshlrev_b32_e32 v38, 16, v63
	v_fma_f32 v4, -v35, v39, 1.0
	v_fmac_f32_e32 v39, v4, v39
	v_div_scale_f32 v4, vcc, v36, v30, v36
	v_mul_f32_e32 v37, v4, v39
	v_fma_f32 v34, -v35, v37, v4
	v_fmac_f32_e32 v37, v34, v39
	v_fma_f32 v4, -v35, v37, v4
	v_mul_f32_e32 v34, 0xbfb8aa3b, v38
	v_mul_f32_e32 v35, 0xbfb8aa3b, v40
	v_exp_f32_e32 v34, v34
	v_exp_f32_e32 v35, v35
	v_div_fmas_f32 v4, v4, v39, v37
	v_div_fixup_f32 v30, v4, v30, v36
	v_pk_mul_f32 v[24:25], v[30:31], v[24:25]
	v_pk_add_f32 v[34:35], v[34:35], 1.0 op_sel_hi:[1,0]
	v_add_f32_dpp v3, v3, v3 quad_perm:[2,3,0,1] row_mask:0xf bank_mask:0xf bound_ctrl:1
	v_div_scale_f32 v4, s[4:5], v35, v35, v40
	v_rcp_f32_e32 v36, v4
	v_cvt_pk_bf16_f32 v22, v24, v25
	v_fma_f32 v26, -v4, v36, 1.0
	v_fmac_f32_e32 v36, v26, v36
	v_div_scale_f32 v26, vcc, v40, v35, v40
	v_mul_f32_e32 v27, v26, v36
	v_fma_f32 v30, -v4, v27, v26
	v_fmac_f32_e32 v27, v30, v36
	v_fma_f32 v4, -v4, v27, v26
	v_div_scale_f32 v26, s[4:5], v34, v34, v38
	v_rcp_f32_e32 v30, v26
	v_div_fmas_f32 v4, v4, v36, v27
	v_div_fixup_f32 v27, v4, v35, v40
	v_fma_f32 v4, -v26, v30, 1.0
	v_fmac_f32_e32 v30, v4, v30
	v_div_scale_f32 v4, vcc, v38, v34, v38
	v_mul_f32_e32 v31, v4, v30
	v_fma_f32 v35, -v26, v31, v4
	v_fmac_f32_e32 v31, v35, v30
	v_fma_f32 v4, -v26, v31, v4
	v_div_fmas_f32 v4, v4, v30, v31
	v_div_fixup_f32 v26, v4, v34, v38
	v_pk_mul_f32 v[26:27], v[26:27], v[32:33]
	v_mov_b32_e32 v4, v5
	v_cvt_pk_bf16_f32 v23, v26, v27
	global_store_dwordx4 v[28:29], v[20:23], off offset:1024
	v_mov_b32_dpp v4, v3 row_half_mirror row_mask:0xf bank_mask:0xf
	s_and_saveexec_b64 s[4:5], s[6:7]
	s_cbranch_execz .LBB0_302
	v_readlane_b32 s8, v242, 38
	v_lshlrev_b64 v[20:21], 6, v[160:161]
	v_readlane_b32 s9, v242, 39
	v_add_f32_e32 v3, v3, v4
	s_nop 0
	v_lshl_add_u64 v[20:21], s[8:9], 0, v[20:21]
	s_lshl_b32 s8, s77, 2
	s_mov_b32 s9, s87
	v_lshl_add_u64 v[20:21], v[20:21], 0, s[8:9]
	global_store_dword v[20:21], v3, off

; #define ATT_WAIT_BAR() asm volatile("s_waitcnt vmcnt(0) lgkmcnt(0)\n\ts_barrier" ::: "memory")
; template <int TYPE>
; __device__ __forceinline__ void epi_preload(EpiPre& e, const Args& a, int l, int h, size_t rowq, int col, int lane) {
;     const int ch = lane & 7;
;     const float* gp = (TYPE == 0 ? a.gn_a : a.gn_b) + (size_t)l * W + h * HD + ch * 8;
;     e.g0 = *(const f32x4*)gp; e.g1 = *(const f32x4*)(gp + 4);
; #pragma unroll
;     for (int i = 0; i < 4; ++i) e.z[i] = *(const u32x4*)((const bf16*)(a.ws + WS_Z) + (rowq + i * 8 + (lane >> 3)) * D + col + ch * 8);
; }
; __device__ __forceinline__ void prompt_unit_sb(const Args& a, int l, int b, int h, int qb, LAS unsigned char* lds) {
;     ...
;     EpiPre pre; epi_preload<1>(pre, a, l, h, rowb + q0 + wid * 32, col, lane);
;     ATT_WAIT_BAR();
.LBB0_1000:
	v_readlane_b32 s8, v242, 12
	v_readlane_b32 s10, v242, 14
	v_readlane_b32 s11, v242, 15
	s_add_u32 s2, s10, s92
	v_readlane_b32 s94, v242, 38
	s_addc_u32 s3, s11, 0
	v_lshlrev_b32_e32 v2, 2, v168
	v_readlane_b32 s95, v242, 39
	global_load_dwordx4 v[6:9], v2, s[2:3] offset:2064
	global_load_dwordx4 v[14:17], v2, s[2:3] offset:2048
	v_lshl_add_u64 v[2:3], s[94:95], 0, v[162:163]
	s_mov_b32 s79, s87
	v_lshl_add_u64 v[2:3], v[2:3], 0, s[78:79]
	v_lshlrev_b32_e32 v4, 1, v168
	v_lshl_add_u64 v[2:3], v[2:3], 0, v[4:5]
	global_load_dwordx4 v[60:63], v[2:3], off offset:1024
	v_readlane_b32 s2, v242, 47
	v_readlane_b32 s3, v242, 48
	s_lshl_b32 s1, s84, 13
	s_add_i32 s1, s1, 0
	v_lshl_add_u64 v[2:3], s[2:3], 0, v[162:163]
	v_lshl_add_u64 v[2:3], v[2:3], 0, s[78:79]
	v_readlane_b32 s2, v237, 9
	v_lshl_add_u64 v[2:3], v[2:3], 0, v[4:5]
	v_readlane_b32 s3, v237, 10
	global_load_dwordx4 v[56:59], v[2:3], off offset:1024
	v_readlane_b32 s96, v242, 30
	v_lshl_add_u64 v[2:3], s[2:3], 0, v[162:163]
	v_lshl_add_u64 v[2:3], v[2:3], 0, s[78:79]
	v_readlane_b32 s2, v237, 5
	v_lshl_add_u64 v[2:3], v[2:3], 0, v[4:5]
	v_readlane_b32 s3, v237, 6
	global_load_dwordx4 v[52:55], v[2:3], off offset:1024
	v_readlane_b32 s97, v242, 31
	v_lshl_add_u64 v[2:3], s[2:3], 0, v[162:163]
	v_lshl_add_u64 v[2:3], v[2:3], 0, s[78:79]
	v_lshl_add_u64 v[2:3], v[2:3], 0, v[4:5]
	global_load_dwordx4 v[10:13], v[2:3], off offset:1024
	v_lshlrev_b32_e32 v2, 2, v169
	v_add3_u32 v2, s1, v171, v2
	v_add_u32_e32 v3, 0x800, v2
	s_waitcnt vmcnt(6) lgkmcnt(0)
	s_barrier
; #define LAS __attribute__((address_space(3)))
; __device__ __forceinline__ float bflo(unsigned w) { return __uint_as_float(w << 16); }
; __device__ __forceinline__ float bfhi(unsigned w) { return __uint_as_float(w & 0xffff0000u); }
; __device__ __forceinline__ int crow(int r, int hi) { return (r & 3) + 8 * (r >> 2) + 4 * hi; }
; __device__ __forceinline__ unsigned cvtpk(float lo, float hi) { f32x2 v = {lo, hi}; bf16x2_t b = __builtin_convertvector(v, bf16x2_t); return __builtin_bit_cast(unsigned, b); }
; #define ATT_LDS_WAIT() asm volatile("s_waitcnt lgkmcnt(0)" ::: "memory")
; __device__ __forceinline__ float gate8(const f32x4& x0, const f32x4& x1, const float (&gn)[8], const u32x4& zw, bf16* orow) {
;     const float zz[8] = {bflo(zw.x), bfhi(zw.x), bflo(zw.y), bfhi(zw.y), bflo(zw.z), bfhi(zw.z), bflo(zw.w), bfhi(zw.w)};
;     const float xs[8] = {x0[0], x0[1], x0[2], x0[3], x1[0], x1[1], x1[2], x1[3]};
;     float r[8], ssq = 0.f;
; #pragma unroll
;     for (int i = 0; i < 8; ++i) { ssq += xs[i] * xs[i]; r[i] = xs[i] * gn[i] * (zz[i] / (1.0f + __expf(-zz[i]))); }
;     u32x4 w; w.x = cvtpk(r[0], r[1]); w.y = cvtpk(r[2], r[3]); w.z = cvtpk(r[4], r[5]); w.w = cvtpk(r[6], r[7]);
;     *(u32x4*)orow = w;
;     return ssq;
; template <int TYPE>
; __device__ __forceinline__ void prompt_epilogue(const Args& a, int l, int h, size_t rowq  , int col, FoxState& st, const EpiPre& pre, LAS float* wsf, LAS float* stg, int lane, int r32, int hi) {
;     ...
; #pragma unroll
;     for (int r = 0; r < 16; ++r) { stg[crow(r, hi) * 64 + r32] = st.o[0][r]; stg[crow(r, hi) * 64 + 32 + r32] = st.o[1][r]; }
;     ATT_LDS_WAIT();
;     const int ch = lane & 7;
;     const float gn[8] = {pre.g0[0], pre.g0[1], pre.g0[2], pre.g0[3], pre.g1[0], pre.g1[1], pre.g1[2], pre.g1[3]};
; #pragma unroll
;     for (int i = 0; i < 4; ++i) {
;         const int row = i * 8 + (lane >> 3); const size_t grow = rowq + row;
;         const f32x4 x0 = *(const LAS f32x4*)(stg + row * 64 + ch * 8), x1 = *(const LAS f32x4*)(stg + row * 64 + ch * 8 + 4);
;         float ssq = gate8(x0, x1, gn, pre.z[i], (bf16*)(a.ws + WS_HN) + grow * D + col + ch * 8);
;         ssq = sum8_dpp(ssq);
;         if (ch == 0) ((float*)(a.ws + WS_SSQ))[grow * 16 + TYPE * 8 + h] = ssq;
;     }
	ds_write2_b32 v2, v20, v36 offset1:32
	ds_write2_b32 v2, v21, v37 offset0:64 offset1:96
	ds_write2_b32 v2, v22, v38 offset0:128 offset1:160
	ds_write2_b32 v2, v23, v39 offset0:192 offset1:224
	ds_write2_b32 v3, v24, v40 offset1:32
	ds_write2_b32 v3, v25, v41 offset0:64 offset1:96
	ds_write2_b32 v3, v26, v42 offset0:128 offset1:160
	ds_write2_b32 v3, v27, v43 offset0:192 offset1:224
	v_add_u32_e32 v3, 0x1000, v2
	v_add_u32_e32 v2, 0x1800, v2
	ds_write2_b32 v3, v28, v44 offset1:32
	ds_write2_b32 v3, v29, v45 offset0:64 offset1:96
	ds_write2_b32 v3, v30, v46 offset0:128 offset1:160
	ds_write2_b32 v3, v31, v47 offset0:192 offset1:224
	ds_write2_b32 v2, v32, v48 offset1:32
	ds_write2_b32 v2, v33, v49 offset0:64 offset1:96
	ds_write2_b32 v2, v34, v50 offset0:128 offset1:160
	ds_write2_b32 v2, v35, v51 offset0:192 offset1:224
	v_and_b32_e32 v28, 7, v19
	v_lshl_add_u32 v19, v28, 5, s1
	s_waitcnt lgkmcnt(0)
	v_lshl_add_u32 v2, v1, 8, v19
	ds_read_b128 v[30:33], v2
	ds_read_b128 v[20:23], v2 offset:16
	v_lshl_add_u64 v[2:3], s[96:97], 0, v[162:163]
	v_lshl_add_u64 v[2:3], v[2:3], 0, s[78:79]
	v_lshlrev_b32_e32 v4, 4, v28
	v_lshl_add_u64 v[2:3], v[2:3], 0, v[4:5]
	s_waitcnt lgkmcnt(1)
	v_mul_f32_e32 v4, v31, v31
	v_fmac_f32_e32 v4, v30, v30
	v_fmac_f32_e32 v4, v32, v32
	v_fmac_f32_e32 v4, v33, v33
	s_waitcnt lgkmcnt(0)
	v_fmac_f32_e32 v4, v20, v20
	v_fmac_f32_e32 v4, v21, v21
	v_fmac_f32_e32 v4, v22, v22
	v_fmac_f32_e32 v4, v23, v23
	v_cmp_eq_u32_e64 s[6:7], 0, v28
	v_readlane_b32 s9, v242, 13
	s_waitcnt vmcnt(5)
	v_pk_mul_f32 v[20:21], v[6:7], v[20:21]
	s_waitcnt vmcnt(4)
	v_pk_mul_f32 v[26:27], v[16:17], v[32:33]
	v_pk_mul_f32 v[30:31], v[14:15], v[30:31]
	s_waitcnt vmcnt(3)
	v_lshlrev_b32_e32 v29, 16, v60
	v_and_b32_e32 v34, 0xffff0000, v60
	v_mul_f32_e32 v24, 0xbfb8aa3b, v29
	v_mul_f32_e32 v25, 0xbfb8aa3b, v34
	v_exp_f32_e32 v24, v24
	v_exp_f32_e32 v25, v25
	v_and_b32_e32 v32, 0xffff0000, v61
	v_pk_add_f32 v[24:25], v[24:25], 1.0 op_sel_hi:[1,0]
	s_nop 0
	v_div_scale_f32 v35, s[2:3], v25, v25, v34
	v_rcp_f32_e32 v36, v35
	s_nop 0
	v_fma_f32 v37, -v35, v36, 1.0
	v_fmac_f32_e32 v36, v37, v36
	v_div_scale_f32 v37, vcc, v34, v25, v34
	v_mul_f32_e32 v38, v37, v36
	v_fma_f32 v39, -v35, v38, v37
	v_fmac_f32_e32 v38, v39, v36
	v_fma_f32 v35, -v35, v38, v37
	v_div_fmas_f32 v35, v35, v36, v38
	v_div_fixup_f32 v25, v35, v25, v34
	v_div_scale_f32 v34, s[2:3], v24, v24, v29
	v_rcp_f32_e32 v35, v34
	s_nop 0
	v_fma_f32 v36, -v34, v35, 1.0
	v_fmac_f32_e32 v35, v36, v35
	v_div_scale_f32 v36, vcc, v29, v24, v29
	v_mul_f32_e32 v37, v36, v35
	v_fma_f32 v38, -v34, v37, v36
	v_fmac_f32_e32 v37, v38, v35
	v_fma_f32 v34, -v34, v37, v36
	v_div_fmas_f32 v34, v34, v35, v37
	v_div_fixup_f32 v24, v34, v24, v29
	v_lshlrev_b32_e32 v29, 16, v61
	v_pk_mul_f32 v[24:25], v[24:25], v[30:31]
	v_mul_f32_e32 v30, 0xbfb8aa3b, v29
	v_mul_f32_e32 v31, 0xbfb8aa3b, v32
	v_exp_f32_e32 v30, v30
	v_exp_f32_e32 v31, v31
	s_nop 0
	v_pk_add_f32 v[30:31], v[30:31], 1.0 op_sel_hi:[1,0]
	s_nop 0
	v_div_scale_f32 v33, s[2:3], v31, v31, v32
	v_rcp_f32_e32 v34, v33
	s_nop 0
	v_fma_f32 v35, -v33, v34, 1.0
	v_fmac_f32_e32 v34, v35, v34
	v_div_scale_f32 v35, vcc, v32, v31, v32
	v_mul_f32_e32 v36, v35, v34
	v_fma_f32 v37, -v33, v36, v35
	v_fmac_f32_e32 v36, v37, v34
	v_fma_f32 v33, -v33, v36, v35
	v_div_fmas_f32 v33, v33, v34, v36
	v_div_fixup_f32 v31, v33, v31, v32
	v_div_scale_f32 v32, s[2:3], v30, v30, v29
	v_rcp_f32_e32 v33, v32
	s_nop 0
	v_fma_f32 v34, -v32, v33, 1.0
	v_fmac_f32_e32 v33, v34, v33
	v_div_scale_f32 v34, vcc, v29, v30, v29
	v_mul_f32_e32 v35, v34, v33
	v_fma_f32 v36, -v32, v35, v34
	v_fmac_f32_e32 v35, v36, v33
	v_fma_f32 v32, -v32, v35, v34
	v_div_fmas_f32 v32, v32, v33, v35
	v_div_fixup_f32 v30, v32, v30, v29
	v_lshlrev_b32_e32 v29, 16, v62
	v_and_b32_e32 v34, 0xffff0000, v62
	v_pk_mul_f32 v[26:27], v[30:31], v[26:27]
	v_mul_f32_e32 v30, 0xbfb8aa3b, v29
	v_mul_f32_e32 v31, 0xbfb8aa3b, v34
	v_exp_f32_e32 v30, v30
	v_exp_f32_e32 v31, v31
	v_pk_mul_f32 v[32:33], v[8:9], v[22:23]
	v_lshlrev_b32_e32 v22, 16, v63
	v_and_b32_e32 v23, 0xffff0000, v63
	v_pk_add_f32 v[30:31], v[30:31], 1.0 op_sel_hi:[1,0]
	s_nop 0
	v_div_scale_f32 v35, s[2:3], v31, v31, v34
	v_rcp_f32_e32 v36, v35
	s_nop 0
	v_fma_f32 v37, -v35, v36, 1.0
	v_fmac_f32_e32 v36, v37, v36
	v_div_scale_f32 v37, vcc, v34, v31, v34
	v_mul_f32_e32 v38, v37, v36
	v_fma_f32 v39, -v35, v38, v37
	v_fmac_f32_e32 v38, v39, v36
	v_fma_f32 v35, -v35, v38, v37
	v_div_fmas_f32 v35, v35, v36, v38
	v_div_fixup_f32 v31, v35, v31, v34
	v_div_scale_f32 v34, s[2:3], v30, v30, v29
	v_rcp_f32_e32 v35, v34
	s_nop 0
	v_fma_f32 v36, -v34, v35, 1.0
	v_fmac_f32_e32 v35, v36, v35
	v_div_scale_f32 v36, vcc, v29, v30, v29
	v_mul_f32_e32 v37, v36, v35
	v_fma_f32 v38, -v34, v37, v36
	v_fmac_f32_e32 v37, v38, v35
	v_fma_f32 v34, -v34, v37, v36
	v_div_fmas_f32 v34, v34, v35, v37
	v_div_fixup_f32 v30, v34, v30, v29
	v_pk_mul_f32 v[30:31], v[30:31], v[20:21]
	v_mul_f32_e32 v20, 0xbfb8aa3b, v22
	v_mul_f32_e32 v21, 0xbfb8aa3b, v23
	v_exp_f32_e32 v20, v20
	v_exp_f32_e32 v21, v21
	s_nop 0
	v_pk_add_f32 v[20:21], v[20:21], 1.0 op_sel_hi:[1,0]
	s_nop 0
	v_div_scale_f32 v29, s[2:3], v21, v21, v23
	v_rcp_f32_e32 v34, v29
	s_nop 0
	v_fma_f32 v35, -v29, v34, 1.0
	v_fmac_f32_e32 v34, v35, v34
	v_div_scale_f32 v35, vcc, v23, v21, v23
	v_mul_f32_e32 v36, v35, v34
	v_fma_f32 v37, -v29, v36, v35
	v_fmac_f32_e32 v36, v37, v34
	v_fma_f32 v29, -v29, v36, v35
	v_div_fmas_f32 v29, v29, v34, v36
	v_div_fixup_f32 v21, v29, v21, v23
	v_div_scale_f32 v23, s[2:3], v20, v20, v22
	v_rcp_f32_e32 v29, v23
	s_nop 0
	v_fma_f32 v34, -v23, v29, 1.0
	v_fmac_f32_e32 v29, v34, v29
	v_div_scale_f32 v34, vcc, v22, v20, v22
	v_mul_f32_e32 v35, v34, v29
	v_fma_f32 v36, -v23, v35, v34
	v_fmac_f32_e32 v35, v36, v29
	v_fma_f32 v23, -v23, v35, v34
	v_div_fmas_f32 v23, v23, v29, v35
	v_div_fixup_f32 v20, v23, v20, v22
	v_pk_mul_f32 v[32:33], v[20:21], v[32:33]
	v_cvt_pk_bf16_f32 v20, v24, v25
	v_cvt_pk_bf16_f32 v21, v26, v27
	v_cvt_pk_bf16_f32 v22, v30, v31
	v_cvt_pk_bf16_f32 v23, v32, v33
	global_store_dwordx4 v[2:3], v[20:23], off offset:1024
	v_add_f32_dpp v2, v4, v4 quad_perm:[1,0,3,2] row_mask:0xf bank_mask:0xf bound_ctrl:1
	v_mov_b32_e32 v3, v5
	s_nop 0
	v_add_f32_dpp v2, v2, v2 quad_perm:[2,3,0,1] row_mask:0xf bank_mask:0xf bound_ctrl:1
	s_nop 1
	v_mov_b32_dpp v3, v2 row_half_mirror row_mask:0xf bank_mask:0xf
	s_and_saveexec_b64 s[2:3], s[6:7]
	v_readlane_b32 s1, v242, 32
	s_cbranch_execz .LBB0_1002
	v_readlane_b32 s8, v242, 36
	v_add_f32_e32 v4, v2, v3
	v_lshlrev_b64 v[2:3], 6, v[160:161]
	v_readlane_b32 s9, v242, 37
	s_nop 1
	v_lshl_add_u64 v[2:3], s[8:9], 0, v[2:3]
	s_lshl_b32 s8, s1, 2
	s_mov_b32 s9, s87
	v_lshl_add_u64 v[2:3], v[2:3], 0, s[8:9]
	global_store_dword v[2:3], v4, off
